# P4a chunk operators: wave-0 16x16 (I-A)^-1 forward substitution rescheduled by hand, all LDS reads of the diagonal blocks batched up front instead of ~30 serial LDS round trips
# speedup vs baseline: 1.0231x; 1.0077x over previous
; __device__ __forceinline__ unsigned pk2(float lo, float hi) { f32x2_t v = {lo, hi}; bf16x2_t b = __builtin_convertvector(v, bf16x2_t); return __builtin_bit_cast(unsigned, b); }
; #define LBAR() do { asm volatile("s_waitcnt lgkmcnt(0)" ::: "memory"); __builtin_amdgcn_s_barrier(); asm volatile("" ::: "memory"); } while (0)
; __device__ __forceinline__ void chunk_item(const PAArgs& A, unsigned char* lds, int item, int tid, int wave, int lane, const ChunkRaw& RAW) {
;     ...
;         c0 = z4; c1 = z4; mm2(KT, AT, ti, tj0, fr, fq, c0, c1);
;         { const f32x4 m0 = S3_MASK(c0, ta, 0), m1 = S3_MASK(c1, tb, 0);
;           *(u32x2*)(AAK + ta * MST + jb) = (u32x2){pk2(m0[0], m0[1]), pk2(m0[2], m0[3])}; *(u32x2*)(AAK + tb * MST + jb) = (u32x2){pk2(m1[0], m1[1]), pk2(m1[2], m1[3])}; }
;         c0 = z4; c1 = z4; mm2(BT, RT, ti, tj0, fr, fq, c0, c1);
;         { const f32x4 m0 = S3_MASK(c0, ta, 1), m1 = S3_MASK(c1, tb, 1);
;           *(u32x2*)(ARB + ta * MST + jb) = (u32x2){pk2(m0[0], m0[1]), pk2(m0[2], m0[3])}; *(u32x2*)(ARB + tb * MST + jb) = (u32x2){pk2(m1[0], m1[1]), pk2(m1[2], m1[3])}; }
;         c0 = z4; c1 = z4; mm2(KT, RT, ti, tj0, fr, fq, c0, c1);
;         { const f32x4 m0 = S3_MASK(c0, ta, 1), m1 = S3_MASK(c1, tb, 1);
;           *(u32x2*)(ARK + ta * MST + jb) = (u32x2){pk2(m0[0], m0[1]), pk2(m0[2], m0[3])}; *(u32x2*)(ARK + tb * MST + jb) = (u32x2){pk2(m1[0], m1[1]), pk2(m1[2], m1[3])}; }
;     ...
;     }
;     LBAR();
;     {
;         f32x4 c0 = z4, c1 = z4;
;         mm2(AAK, VT, ti, tj0, fr, fq, c0, c1);
;         *(u32x2*)(AVT + (tj0 * 16 + fr) * MST + ti * 16 + fq * 4) = (u32x2){pk2(c0[0], c0[1]), pk2(c0[2], c0[3])};
;         *(u32x2*)(AVT + (tj0 * 16 + 16 + fr) * MST + ti * 16 + fq * 4) = (u32x2){pk2(c1[0], c1[1]), pk2(c1[2], c1[3])};
.LBB0_435:
	ds_read_b128 v[0:3], v52 offset:18432
	ds_read_b128 v[4:7], v53
	ds_read_b128 v[18:21], v53 offset:2304
	ds_read_b128 v[116:119], v52 offset:18496
	s_and_b64 vcc, exec, s[6:7]
	s_waitcnt lgkmcnt(2)
	v_mfma_f32_16x16x32_bf16 v[4:7], v[0:3], v[4:7], 0
	s_waitcnt lgkmcnt(1)
	v_mfma_f32_16x16x32_bf16 v[0:3], v[0:3], v[18:21], 0
	ds_read_b128 v[18:21], v53 offset:64
	s_waitcnt lgkmcnt(0)
	v_mfma_f32_16x16x32_bf16 v[4:7], v[116:119], v[18:21], v[4:7]
	ds_read_b128 v[18:21], v53 offset:2368
	s_waitcnt lgkmcnt(0)
	v_mfma_f32_16x16x32_bf16 v[0:3], v[116:119], v[18:21], v[0:3]
	s_nop 4
	v_cndmask_b32_e64 v4, 0, v4, s[54:55]
	v_cndmask_b32_e64 v5, 0, v5, s[22:23]
	v_cndmask_b32_e64 v6, 0, v6, s[20:21]
	v_cndmask_b32_e64 v7, 0, v7, s[56:57]
	v_cndmask_b32_e64 v18, 0, v0, s[58:59]
	v_cndmask_b32_e64 v19, 0, v1, s[60:61]
	v_cndmask_b32_e64 v2, 0, v2, s[62:63]
	v_cndmask_b32_e64 v3, 0, v3, s[64:65]
	v_cvt_pk_bf16_f32 v0, v4, v5
	v_cvt_pk_bf16_f32 v1, v6, v7
	ds_write_b64 v77, v[0:1] offset:64512
	v_cvt_pk_bf16_f32 v0, v18, v19
	v_cvt_pk_bf16_f32 v1, v2, v3
	ds_write_b64 v78, v[0:1] offset:64512
	ds_read_b128 v[0:3], v52 offset:9216
	ds_read_b128 v[4:7], v53 offset:27648
	ds_read_b128 v[18:21], v53 offset:29952
	ds_read_b128 v[116:119], v52 offset:9280
	s_waitcnt lgkmcnt(2)
	v_mfma_f32_16x16x32_bf16 v[4:7], v[0:3], v[4:7], 0
	s_waitcnt lgkmcnt(1)
	v_mfma_f32_16x16x32_bf16 v[0:3], v[0:3], v[18:21], 0
	ds_read_b128 v[18:21], v53 offset:27712
	s_waitcnt lgkmcnt(0)
	v_mfma_f32_16x16x32_bf16 v[4:7], v[116:119], v[18:21], v[4:7]
	ds_read_b128 v[18:21], v53 offset:30016
	s_waitcnt lgkmcnt(0)
	v_mfma_f32_16x16x32_bf16 v[0:3], v[116:119], v[18:21], v[0:3]
	s_nop 4
	v_cndmask_b32_e64 v4, v4, 0, s[66:67]
	v_cndmask_b32_e64 v5, 0, v5, s[54:55]
	v_cndmask_b32_e64 v6, v6, 0, s[72:73]
	v_cndmask_b32_e64 v7, v7, 0, s[16:17]
	v_cndmask_b32_e64 v18, 0, v0, s[76:77]
	v_cndmask_b32_e64 v19, 0, v1, s[78:79]
	v_cndmask_b32_e64 v2, 0, v2, s[80:81]
	v_cndmask_b32_e64 v3, 0, v3, s[82:83]
	v_cvt_pk_bf16_f32 v0, v4, v5
	v_cvt_pk_bf16_f32 v1, v6, v7
	ds_write_b64 v83, v[0:1]
	v_cvt_pk_bf16_f32 v0, v18, v19
	v_cvt_pk_bf16_f32 v1, v2, v3
	ds_write_b64 v84, v[0:1]
	ds_read_b128 v[0:3], v52 offset:18432
	ds_read_b128 v[4:7], v53 offset:27648
	ds_read_b128 v[18:21], v53 offset:29952
	ds_read_b128 v[116:119], v52 offset:18496
	s_waitcnt lgkmcnt(2)
	v_mfma_f32_16x16x32_bf16 v[4:7], v[0:3], v[4:7], 0
	s_waitcnt lgkmcnt(1)
	v_mfma_f32_16x16x32_bf16 v[0:3], v[0:3], v[18:21], 0
	ds_read_b128 v[18:21], v53 offset:27712
	s_waitcnt lgkmcnt(0)
	v_mfma_f32_16x16x32_bf16 v[4:7], v[116:119], v[18:21], v[4:7]
	ds_read_b128 v[18:21], v53 offset:30016
	s_waitcnt lgkmcnt(0)
	v_mfma_f32_16x16x32_bf16 v[0:3], v[116:119], v[18:21], v[0:3]
	s_nop 4
	v_cndmask_b32_e64 v4, v4, 0, s[66:67]
	v_cndmask_b32_e64 v5, 0, v5, s[54:55]
	v_cndmask_b32_e64 v6, v6, 0, s[72:73]
	v_cndmask_b32_e64 v7, v7, 0, s[16:17]
	v_cndmask_b32_e64 v18, 0, v0, s[76:77]
	v_cndmask_b32_e64 v19, 0, v1, s[78:79]
	v_cndmask_b32_e64 v2, 0, v2, s[80:81]
	v_cndmask_b32_e64 v3, 0, v3, s[82:83]
	v_cvt_pk_bf16_f32 v0, v4, v5
	v_cvt_pk_bf16_f32 v1, v6, v7
	ds_write_b64 v85, v[0:1]
	v_cvt_pk_bf16_f32 v0, v18, v19
	v_cvt_pk_bf16_f32 v1, v2, v3
	ds_write_b64 v86, v[0:1]
	s_waitcnt lgkmcnt(0)
	s_barrier
	ds_read_b128 v[0:3], v52 offset:64512
	ds_read_b128 v[4:7], v53 offset:55296
	ds_read_b128 v[18:21], v53 offset:57600
	ds_read_b128 v[116:119], v52 offset:64576
	s_waitcnt lgkmcnt(2)
	v_mfma_f32_16x16x32_bf16 v[4:7], v[0:3], v[4:7], 0
	s_waitcnt lgkmcnt(1)
	v_mfma_f32_16x16x32_bf16 v[0:3], v[0:3], v[18:21], 0
	ds_read_b128 v[18:21], v53 offset:55360
	s_waitcnt lgkmcnt(0)
	v_mfma_f32_16x16x32_bf16 v[4:7], v[116:119], v[18:21], v[4:7]
	ds_read_b128 v[18:21], v53 offset:57664
	s_waitcnt lgkmcnt(0)
	v_mfma_f32_16x16x32_bf16 v[0:3], v[116:119], v[18:21], v[0:3]
	s_nop 4
	v_cvt_pk_bf16_f32 v4, v4, v5
	v_cvt_pk_bf16_f32 v5, v6, v7
	ds_write_b64 v57, v[4:5]
	v_cvt_pk_bf16_f32 v0, v0, v1
	v_cvt_pk_bf16_f32 v1, v2, v3
	ds_write_b64 v57, v[0:1] offset:2304
	s_cbranch_vccnz .LBB0_428
; __device__ __forceinline__ unsigned f2bf(float f) { return pk2(f, f) & 0xffffu; }
; __device__ __forceinline__ void chunk_item(const PAArgs& A, unsigned char* lds, int item, int tid, int wave, int lane, const ChunkRaw& RAW) {
;     ...
;         if (wave == 0) {
;             const int bi = lane >> 4, cc = lane & 15;
;             float t[16];
; #pragma unroll
;             for (int r = 0; r < 16; ++r) {
;                 float acc = (r == cc) ? 1.f : 0.f;
; #pragma unroll
;                 for (int k = 0; k < r; ++k) acc += Dg[(bi * 16 + r) * 16 + k] * t[k];
;                 t[r] = acc;
;             }
; #pragma unroll
;             for (int r = 0; r < 16; ++r) Tinv[(bi * 16 + r) * TST + cc] = (bf16)f2bf(t[r]);
;         }
	ds_write_b16 v95, v87
	ds_read_b32 v116, v58 offset:64
	ds_read_b64 v[120:121], v58 offset:128
	ds_read_b96 v[124:126], v58 offset:192
	ds_read_b128 v[128:131], v58 offset:256
	ds_read_b128 v[132:135], v58 offset:320
	ds_read_b32 v136, v58 offset:336
	ds_read_b128 v[140:143], v58 offset:384
	ds_read_b64 v[144:145], v58 offset:400
	ds_read_b128 v[148:151], v58 offset:448
	ds_read_b96 v[152:154], v58 offset:464
	ds_read_b128 v[156:159], v58 offset:512
	ds_read_b128 v[160:163], v58 offset:528
	ds_read_b128 v[164:167], v58 offset:576
	ds_read_b128 v[168:171], v58 offset:592
	ds_read_b32 v172, v58 offset:608
	ds_read_b128 v[176:179], v58 offset:640
	ds_read_b128 v[180:183], v58 offset:656
	ds_read_b64 v[184:185], v58 offset:672
	ds_read_b128 v[188:191], v58 offset:704
	ds_read_b128 v[192:195], v58 offset:720
	ds_read_b96 v[196:198], v58 offset:736
	ds_read_b128 v[200:203], v58 offset:768
	ds_read_b128 v[204:207], v58 offset:784
	ds_read_b128 v[208:211], v58 offset:800
	ds_read_b128 v[212:215], v58 offset:832
	ds_read_b128 v[216:219], v58 offset:848
	ds_read_b128 v[220:223], v58 offset:864
	ds_read_b32 v224, v58 offset:880
	ds_read_b128 v[226:229], v58 offset:896
	ds_read_b128 v[230:233], v58 offset:912
	ds_read_b128 v[234:237], v58 offset:928
	ds_read_b64 v[238:239], v58 offset:944
	s_waitcnt lgkmcnt(15)
	v_fma_f32 v0, v54, v116, v55
	s_waitcnt lgkmcnt(15)
	v_fma_f32 v1, v54, v120, v59
	v_fmac_f32_e32 v1, v0, v121
	s_waitcnt lgkmcnt(15)
	v_fma_f32 v2, v54, v124, v60
	v_fmac_f32_e32 v2, v0, v125
	v_fmac_f32_e32 v2, v1, v126
	s_waitcnt lgkmcnt(15)
	v_fma_f32 v3, v54, v128, v61
	v_fmac_f32_e32 v3, v0, v129
	v_fmac_f32_e32 v3, v1, v130
	v_fmac_f32_e32 v3, v2, v131
	s_waitcnt lgkmcnt(15)
	v_fma_f32 v4, v54, v132, v62
	v_fmac_f32_e32 v4, v0, v133
	v_fmac_f32_e32 v4, v1, v134
	v_fmac_f32_e32 v4, v2, v135
	v_fmac_f32_e32 v4, v3, v136
	s_waitcnt lgkmcnt(15)
	v_fma_f32 v5, v54, v140, v63
	v_fmac_f32_e32 v5, v0, v141
	v_fmac_f32_e32 v5, v1, v142
	v_fmac_f32_e32 v5, v2, v143
	v_fmac_f32_e32 v5, v3, v144
	v_fmac_f32_e32 v5, v4, v145
	s_waitcnt lgkmcnt(15)
	v_fma_f32 v6, v54, v148, v64
	v_fmac_f32_e32 v6, v0, v149
	v_fmac_f32_e32 v6, v1, v150
	v_fmac_f32_e32 v6, v2, v151
	v_fmac_f32_e32 v6, v3, v152
	v_fmac_f32_e32 v6, v4, v153
	v_fmac_f32_e32 v6, v5, v154
	s_waitcnt lgkmcnt(15)
	v_fma_f32 v7, v54, v156, v65
	v_fmac_f32_e32 v7, v0, v157
	v_fmac_f32_e32 v7, v1, v158
	v_fmac_f32_e32 v7, v2, v159
	v_fmac_f32_e32 v7, v3, v160
	v_fmac_f32_e32 v7, v4, v161
	v_fmac_f32_e32 v7, v5, v162
	v_fmac_f32_e32 v7, v6, v163
	s_waitcnt lgkmcnt(15)
	v_fma_f32 v18, v54, v164, v66
	v_fmac_f32_e32 v18, v0, v165
	v_fmac_f32_e32 v18, v1, v166
	v_fmac_f32_e32 v18, v2, v167
	v_fmac_f32_e32 v18, v3, v168
	v_fmac_f32_e32 v18, v4, v169
	v_fmac_f32_e32 v18, v5, v170
	v_fmac_f32_e32 v18, v6, v171
	v_fmac_f32_e32 v18, v7, v172
	s_waitcnt lgkmcnt(14)
	v_fma_f32 v19, v54, v176, v67
	v_fmac_f32_e32 v19, v0, v177
	v_fmac_f32_e32 v19, v1, v178
	v_fmac_f32_e32 v19, v2, v179
	v_fmac_f32_e32 v19, v3, v180
	v_fmac_f32_e32 v19, v4, v181
	v_fmac_f32_e32 v19, v5, v182
	v_fmac_f32_e32 v19, v6, v183
	v_fmac_f32_e32 v19, v7, v184
	v_fmac_f32_e32 v19, v18, v185
	ds_read_b128 v[116:119], v58 offset:960
	ds_read_b128 v[120:123], v58 offset:976
	ds_read_b128 v[124:127], v58 offset:992
	ds_read_b96 v[128:130], v58 offset:1008
	s_waitcnt lgkmcnt(15)
	v_fma_f32 v20, v54, v188, v68
	v_fmac_f32_e32 v20, v0, v189
	v_fmac_f32_e32 v20, v1, v190
	v_fmac_f32_e32 v20, v2, v191
	v_fmac_f32_e32 v20, v3, v192
	v_fmac_f32_e32 v20, v4, v193
	v_fmac_f32_e32 v20, v5, v194
	v_fmac_f32_e32 v20, v6, v195
	v_fmac_f32_e32 v20, v7, v196
	v_fmac_f32_e32 v20, v18, v197
	v_fmac_f32_e32 v20, v19, v198
	s_waitcnt lgkmcnt(12)
	v_fma_f32 v21, v54, v200, v69
	v_fmac_f32_e32 v21, v0, v201
	v_fmac_f32_e32 v21, v1, v202
	v_fmac_f32_e32 v21, v2, v203
	v_fmac_f32_e32 v21, v3, v204
	v_fmac_f32_e32 v21, v4, v205
	v_fmac_f32_e32 v21, v5, v206
	v_fmac_f32_e32 v21, v6, v207
	v_fmac_f32_e32 v21, v7, v208
	v_fmac_f32_e32 v21, v18, v209
	v_fmac_f32_e32 v21, v19, v210
	v_fmac_f32_e32 v21, v20, v211
	s_waitcnt lgkmcnt(8)
	v_fma_f32 v115, v54, v212, v70
	v_fmac_f32_e32 v115, v0, v213
	v_fmac_f32_e32 v115, v1, v214
	v_fmac_f32_e32 v115, v2, v215
	v_fmac_f32_e32 v115, v3, v216
	v_fmac_f32_e32 v115, v4, v217
	v_fmac_f32_e32 v115, v5, v218
	v_fmac_f32_e32 v115, v6, v219
	v_fmac_f32_e32 v115, v7, v220
	v_fmac_f32_e32 v115, v18, v221
	v_fmac_f32_e32 v115, v19, v222
	v_fmac_f32_e32 v115, v20, v223
	v_fmac_f32_e32 v115, v21, v224
	s_waitcnt lgkmcnt(4)
	v_fma_f32 v132, v54, v226, v71
	v_fmac_f32_e32 v132, v0, v227
	v_fmac_f32_e32 v132, v1, v228
	v_fmac_f32_e32 v132, v2, v229
	v_fmac_f32_e32 v132, v3, v230
	v_fmac_f32_e32 v132, v4, v231
	v_fmac_f32_e32 v132, v5, v232
	v_fmac_f32_e32 v132, v6, v233
	v_fmac_f32_e32 v132, v7, v234
	v_fmac_f32_e32 v132, v18, v235
	v_fmac_f32_e32 v132, v19, v236
	v_fmac_f32_e32 v132, v20, v237
	v_fmac_f32_e32 v132, v21, v238
	v_fmac_f32_e32 v132, v115, v239
	s_waitcnt lgkmcnt(0)
	v_fma_f32 v133, v54, v116, v72
	v_fmac_f32_e32 v133, v0, v117
	v_fmac_f32_e32 v133, v1, v118
	v_fmac_f32_e32 v133, v2, v119
	v_fmac_f32_e32 v133, v3, v120
	v_fmac_f32_e32 v133, v4, v121
	v_fmac_f32_e32 v133, v5, v122
	v_fmac_f32_e32 v133, v6, v123
	v_fmac_f32_e32 v133, v7, v124
	v_fmac_f32_e32 v133, v18, v125
	v_fmac_f32_e32 v133, v19, v126
	v_fmac_f32_e32 v133, v20, v127
	v_fmac_f32_e32 v133, v21, v128
	v_fmac_f32_e32 v133, v115, v129
	v_fmac_f32_e32 v133, v132, v130
	v_cvt_pk_bf16_f32 v135, v0, s0
	ds_write_b16 v95, v135 offset:40
	v_cvt_pk_bf16_f32 v134, v1, s0
	ds_write_b16 v95, v134 offset:80
	v_cvt_pk_bf16_f32 v135, v2, s0
	ds_write_b16 v95, v135 offset:120
	v_cvt_pk_bf16_f32 v134, v3, s0
	ds_write_b16 v95, v134 offset:160
	v_cvt_pk_bf16_f32 v135, v4, s0
	ds_write_b16 v95, v135 offset:200
	v_cvt_pk_bf16_f32 v134, v5, s0
	ds_write_b16 v95, v134 offset:240
	v_cvt_pk_bf16_f32 v135, v6, s0
	ds_write_b16 v95, v135 offset:280
	v_cvt_pk_bf16_f32 v134, v7, s0
	ds_write_b16 v95, v134 offset:320
	v_cvt_pk_bf16_f32 v135, v18, s0
	ds_write_b16 v95, v135 offset:360
	v_cvt_pk_bf16_f32 v134, v19, s0
	ds_write_b16 v95, v134 offset:400
	v_cvt_pk_bf16_f32 v135, v20, s0
	ds_write_b16 v95, v135 offset:440
	v_cvt_pk_bf16_f32 v134, v21, s0
	ds_write_b16 v95, v134 offset:480
	v_cvt_pk_bf16_f32 v135, v115, s0
	ds_write_b16 v95, v135 offset:520
	v_cvt_pk_bf16_f32 v134, v132, s0
	ds_write_b16 v95, v134 offset:560
	v_cvt_pk_bf16_f32 v135, v133, s0
	ds_write_b16 v96, v135
	s_branch .LBB0_428
